# attention epilogue: row-per-lane dwordx2 stores widened to dwordx4 with v_permlane32_swap
# speedup vs baseline: 1.0104x; 1.0104x over previous
; DI unsigned pk2(float a, float b) { f32x2 v = {a, b}; bf16v2 r = __builtin_convertvector(v, bf16v2); return __builtin_bit_cast(unsigned, r); }
; __device__ __forceinline__ void attn_phase(LAS unsigned char* ldsb, bf16_t* P, const bf16_t* Kn, const bf16_t* KPE, const bf16_t* VT) {
;     ...
;             const float ltot = lrun + __shfl_xor(lrun, 32);
;             const float inv = 1.0f / ltot;
;             bf16_t* op = P + (rowbase + qabs) * LDP + 3072 + h * 128;
; #pragma unroll
;             for (int d = 0; d < 4; ++d)
; #pragma unroll
;                 for (int g4 = 0; g4 < 4; ++g4) { u32x2 pw; pw.x = pk2(o[d][g4 * 4] * inv, o[d][g4 * 4 + 1] * inv); pw.y = pk2(o[d][g4 * 4 + 2] * inv, o[d][g4 * 4 + 3] * inv);
;                     *(u32x2*)(op + d * 32 + 8 * g4 + 4 * hh) = pw; }
.LBB0_1511:
	v_cmp_lt_i32_e32 vcc, v0, v3
	s_mov_b64 s[76:77], 0
	s_nop 0
	v_cndmask_b32_e32 v0, v2, v0, vcc
	v_lshlrev_b32_e32 v0, 2, v0
	ds_bpermute_b32 v0, v0, v4
	v_lshl_add_u64 v[2:3], v[226:227], 0, s[16:17]
	s_waitcnt lgkmcnt(0)
	v_add_f32_e32 v4, v4, v0
	v_div_scale_f32 v5, s[6:7], v4, v4, 1.0
	v_rcp_f32_e32 v6, v5
	v_div_scale_f32 v7, vcc, 1.0, v4, 1.0
	v_lshlrev_b32_e32 v0, 1, v229
	v_fma_f32 v8, -v5, v6, 1.0
	v_fmac_f32_e32 v6, v8, v6
	v_mul_f32_e32 v8, v7, v6
	v_fma_f32 v9, -v5, v8, v7
	v_fmac_f32_e32 v8, v9, v6
	v_fma_f32 v5, -v5, v8, v7
	v_div_fmas_f32 v5, v5, v6, v8
	v_div_fixup_f32 v4, v5, v4, 1.0
	v_lshl_add_u64 v[2:3], v[2:3], 0, v[0:1]
	v_lshl_add_u64 v[6:7], v[2:3], 0, s[58:59]
	v_lshl_add_u64 v[6:7], v[6:7], 0, v[0:1]
	v_pk_mul_f32 v[16:17], v[160:161], v[4:5] op_sel_hi:[1,0]
	v_pk_mul_f32 v[18:19], v[162:163], v[4:5] op_sel_hi:[1,0]
	v_pk_mul_f32 v[20:21], v[164:165], v[4:5] op_sel_hi:[1,0]
	v_pk_mul_f32 v[22:23], v[166:167], v[4:5] op_sel_hi:[1,0]
	v_cvt_pk_bf16_f32 v8, v16, v17
	v_cvt_pk_bf16_f32 v9, v18, v19
	v_cvt_pk_bf16_f32 v10, v20, v21
	v_cvt_pk_bf16_f32 v11, v22, v23
	s_nop 1
	v_permlane32_swap_b32_e32 v8, v10
	v_permlane32_swap_b32_e32 v9, v11
	global_store_dwordx4 v[6:7], v[8:11], off offset:0
	v_pk_mul_f32 v[16:17], v[168:169], v[4:5] op_sel_hi:[1,0]
	v_pk_mul_f32 v[18:19], v[170:171], v[4:5] op_sel_hi:[1,0]
	v_pk_mul_f32 v[20:21], v[172:173], v[4:5] op_sel_hi:[1,0]
	v_pk_mul_f32 v[22:23], v[174:175], v[4:5] op_sel_hi:[1,0]
	v_cvt_pk_bf16_f32 v12, v16, v17
	v_cvt_pk_bf16_f32 v13, v18, v19
	v_cvt_pk_bf16_f32 v14, v20, v21
	v_cvt_pk_bf16_f32 v15, v22, v23
	s_nop 1
	v_permlane32_swap_b32_e32 v12, v14
	v_permlane32_swap_b32_e32 v13, v15
	global_store_dwordx4 v[6:7], v[12:15], off offset:32
	v_pk_mul_f32 v[16:17], v[144:145], v[4:5] op_sel_hi:[1,0]
	v_pk_mul_f32 v[18:19], v[146:147], v[4:5] op_sel_hi:[1,0]
	v_pk_mul_f32 v[20:21], v[148:149], v[4:5] op_sel_hi:[1,0]
	v_pk_mul_f32 v[22:23], v[150:151], v[4:5] op_sel_hi:[1,0]
	v_cvt_pk_bf16_f32 v8, v16, v17
	v_cvt_pk_bf16_f32 v9, v18, v19
	v_cvt_pk_bf16_f32 v10, v20, v21
	v_cvt_pk_bf16_f32 v11, v22, v23
	s_nop 1
	v_permlane32_swap_b32_e32 v8, v10
	v_permlane32_swap_b32_e32 v9, v11
	global_store_dwordx4 v[6:7], v[8:11], off offset:64
	v_pk_mul_f32 v[16:17], v[152:153], v[4:5] op_sel_hi:[1,0]
	v_pk_mul_f32 v[18:19], v[154:155], v[4:5] op_sel_hi:[1,0]
	v_pk_mul_f32 v[20:21], v[156:157], v[4:5] op_sel_hi:[1,0]
	v_pk_mul_f32 v[22:23], v[158:159], v[4:5] op_sel_hi:[1,0]
	v_cvt_pk_bf16_f32 v12, v16, v17
	v_cvt_pk_bf16_f32 v13, v18, v19
	v_cvt_pk_bf16_f32 v14, v20, v21
	v_cvt_pk_bf16_f32 v15, v22, v23
	s_nop 1
	v_permlane32_swap_b32_e32 v12, v14
	v_permlane32_swap_b32_e32 v13, v15
	global_store_dwordx4 v[6:7], v[12:15], off offset:96
	v_pk_mul_f32 v[16:17], v[128:129], v[4:5] op_sel_hi:[1,0]
	v_pk_mul_f32 v[18:19], v[130:131], v[4:5] op_sel_hi:[1,0]
	v_pk_mul_f32 v[20:21], v[132:133], v[4:5] op_sel_hi:[1,0]
	v_pk_mul_f32 v[22:23], v[134:135], v[4:5] op_sel_hi:[1,0]
	v_cvt_pk_bf16_f32 v8, v16, v17
	v_cvt_pk_bf16_f32 v9, v18, v19
	v_cvt_pk_bf16_f32 v10, v20, v21
	v_cvt_pk_bf16_f32 v11, v22, v23
	s_nop 1
	v_permlane32_swap_b32_e32 v8, v10
	v_permlane32_swap_b32_e32 v9, v11
	global_store_dwordx4 v[6:7], v[8:11], off offset:128
	v_pk_mul_f32 v[16:17], v[136:137], v[4:5] op_sel_hi:[1,0]
	v_pk_mul_f32 v[18:19], v[138:139], v[4:5] op_sel_hi:[1,0]
	v_pk_mul_f32 v[20:21], v[140:141], v[4:5] op_sel_hi:[1,0]
	v_pk_mul_f32 v[22:23], v[142:143], v[4:5] op_sel_hi:[1,0]
	v_cvt_pk_bf16_f32 v12, v16, v17
	v_cvt_pk_bf16_f32 v13, v18, v19
	v_cvt_pk_bf16_f32 v14, v20, v21
	v_cvt_pk_bf16_f32 v15, v22, v23
	s_nop 1
	v_permlane32_swap_b32_e32 v12, v14
	v_permlane32_swap_b32_e32 v13, v15
	global_store_dwordx4 v[6:7], v[12:15], off offset:160
	v_pk_mul_f32 v[16:17], v[112:113], v[4:5] op_sel_hi:[1,0]
	v_pk_mul_f32 v[18:19], v[114:115], v[4:5] op_sel_hi:[1,0]
	v_pk_mul_f32 v[20:21], v[116:117], v[4:5] op_sel_hi:[1,0]
	v_pk_mul_f32 v[22:23], v[118:119], v[4:5] op_sel_hi:[1,0]
	v_cvt_pk_bf16_f32 v8, v16, v17
	v_cvt_pk_bf16_f32 v9, v18, v19
	v_cvt_pk_bf16_f32 v10, v20, v21
	v_cvt_pk_bf16_f32 v11, v22, v23
	s_nop 1
	v_permlane32_swap_b32_e32 v8, v10
	v_permlane32_swap_b32_e32 v9, v11
	global_store_dwordx4 v[6:7], v[8:11], off offset:192
	v_pk_mul_f32 v[16:17], v[120:121], v[4:5] op_sel_hi:[1,0]
	v_pk_mul_f32 v[18:19], v[122:123], v[4:5] op_sel_hi:[1,0]
	v_pk_mul_f32 v[20:21], v[124:125], v[4:5] op_sel_hi:[1,0]
	v_pk_mul_f32 v[22:23], v[126:127], v[4:5] op_sel_hi:[1,0]
	v_cvt_pk_bf16_f32 v12, v16, v17
	v_cvt_pk_bf16_f32 v13, v18, v19
	v_cvt_pk_bf16_f32 v14, v20, v21
	v_cvt_pk_bf16_f32 v15, v22, v23
	s_nop 1
	v_permlane32_swap_b32_e32 v12, v14
	v_permlane32_swap_b32_e32 v13, v15
	s_and_b64 vcc, exec, s[74:75]
	global_store_dwordx4 v[6:7], v[12:15], off offset:224
	s_cbranch_vccnz .LBB0_1509
